# attention row-sum packed adds restructured as a tree on top of v43
# speedup vs baseline: 1.0004x; 1.0004x over previous
; DI void attn_job(const Params& p, int l, int bk, int qt, char* smem) {
;     ...
;     float ps0 = 0.f, ps1 = 0.f;
; #pragma unroll
;     for (int i = 0; i < 16; ++i) {
;       st[0][0][i] = __builtin_amdgcn_exp2f(st[0][0][i]); st[0][1][i] = __builtin_amdgcn_exp2f(st[0][1][i]);
;       st[1][0][i] = __builtin_amdgcn_exp2f(st[1][0][i]); st[1][1][i] = __builtin_amdgcn_exp2f(st[1][1][i]);
;       ps0 += st[0][0][i] + st[0][1][i]; ps1 += st[1][0][i] + st[1][1][i];
;     }
;     lp0 += ps0; lp1 += ps1;
;     ...
;     __syncthreads();
.LBB0_614:
	v_add_f32_e32 v94, v205, v141
	v_add_f32_e32 v94, 0, v94
	v_add_f32_e32 v95, v209, v137
	v_add_f32_e32 v104, v243, v138
	v_add_f32_e32 v94, v104, v94
	v_add_f32_e32 v104, v244, v126
	v_add_f32_e32 v105, v245, v142
	v_add_f32_e32 v95, 0, v95
	v_add_f32_e32 v94, v105, v94
	v_add_f32_e32 v105, v246, v139
	v_add_f32_e32 v106, v247, v140
	v_add_f32_e32 v95, v104, v95
	v_add_f32_e32 v94, v106, v94
	v_add_f32_e32 v106, v248, v127
	v_add_f32_e32 v107, v132, v136
	v_add_f32_e32 v95, v105, v95
	v_add_f32_e32 v94, v107, v94
	v_add_f32_e32 v107, v249, v100
	v_add_f32_e32 v95, v106, v95
	v_add_f32_e32 v100, v250, v143
	v_add_f32_e32 v103, v135, v103
	v_add_f32_e32 v95, v107, v95
	v_add_f32_e32 v94, v100, v94
	v_add_f32_e32 v100, v133, v101
	v_add_f32_e32 v101, v134, v102
	v_add_f32_e32 v95, v103, v95
	v_pk_add_f32 v[80:81], v[112:113], v[80:81]
	v_pk_add_f32 v[96:97], v[114:115], v[96:97]
	v_pk_add_f32 v[98:99], v[116:117], v[98:99]
	v_pk_add_f32 v[88:89], v[128:129], v[88:89]
	v_pk_add_f32 v[90:91], v[130:131], v[90:91]
	v_pk_add_f32 v[84:85], v[120:121], v[84:85]
	v_pk_add_f32 v[92:93], v[124:125], v[92:93]
	v_pk_add_f32 v[82:83], v[118:119], v[82:83]
	v_pk_add_f32 v[86:87], v[122:123], v[86:87]
	v_pk_add_f32 v[94:95], v[100:101], v[94:95]
	v_pk_add_f32 v[96:97], v[96:97], v[98:99]
	v_pk_add_f32 v[88:89], v[88:89], v[90:91]
	v_pk_add_f32 v[84:85], v[84:85], v[92:93]
	v_pk_add_f32 v[82:83], v[82:83], v[86:87]
	v_pk_add_f32 v[80:81], v[80:81], v[94:95]
	s_mov_b64 s[6:7], 0x80
	v_pk_add_f32 v[88:89], v[88:89], v[84:85]
	v_pk_add_f32 v[80:81], v[80:81], v[96:97]
	v_lshl_add_u64 v[212:213], v[212:213], 0, s[90:91]
	v_pk_add_f32 v[80:81], v[80:81], v[88:89]
	v_lshl_add_u64 v[214:215], v[214:215], 0, s[6:7]
	v_pk_add_f32 v[80:81], v[80:81], v[82:83]
	s_cmp_lg_u32 s4, s2
	s_mov_b32 s5, s2
	v_pk_add_f32 v[206:207], v[206:207], v[80:81]
	s_waitcnt lgkmcnt(0)
	s_barrier
	s_cbranch_scc0 .LBB0_606
